# R3 epilogue gate loads hoisted, R3 mid-stage wait removed, transpose scale loads batched
# speedup vs baseline: 1.0041x; 1.0041x over previous
.LBB0_59:
	s_lshr_b32 s18, s86, 8
	v_cvt_f32_u32_e32 v32, s18
	s_sub_i32 s19, 0, s18
	s_abs_i32 s1, s81
	s_ashr_i32 s0, s81, 31
	v_rcp_iflag_f32_e32 v32, v32
	v_mov_b32_e32 v33, 1.0
	s_barrier
	v_mul_f32_e32 v32, 0x4f7ffffe, v32
	v_cvt_u32_f32_e32 v32, v32
	s_nop 0
	v_readfirstlane_b32 s34, v32
	s_mul_i32 s19, s19, s34
	s_mul_hi_u32 s19, s34, s19
	s_add_i32 s34, s34, s19
	s_mul_hi_u32 s19, s1, s34
	s_mul_i32 s34, s19, s18
	s_sub_i32 s1, s1, s34
	s_add_i32 s35, s19, 1
	s_sub_i32 s34, s1, s18
	s_cmp_ge_u32 s1, s18
	s_cselect_b32 s19, s35, s19
	s_cselect_b32 s1, s34, s1
	s_add_i32 s34, s19, 1
	s_cmp_ge_u32 s1, s18
	s_cselect_b32 s1, s34, s19
	s_xor_b32 s1, s1, s0
	s_sub_i32 s19, s1, s0
	s_lshl_b32 s80, s19, 6
	s_cmp_lg_u64 s[4:5], 0
	s_cselect_b64 s[82:83], -1, 0
	s_add_i32 s78, s80, s3
	s_cmp_eq_u64 s[4:5], 0
	v_mov_b32_e32 v32, 1.0
	s_cbranch_scc1 .LBB0_61
	s_ashr_i32 s79, s78, 31
	s_lshl_b64 s[0:1], s[78:79], 2
	s_add_u32 s0, s4, s0
	s_addc_u32 s1, s5, s1
	global_load_dword v33, v41, s[0:1]
	global_load_dword v101, v41, s[0:1] offset:32
	global_load_dword v102, v41, s[0:1] offset:64
	global_load_dword v103, v41, s[0:1] offset:96
	global_load_dword v104, v41, s[0:1] offset:128
	global_load_dword v105, v41, s[0:1] offset:160
	global_load_dword v106, v41, s[0:1] offset:192
	global_load_dword v107, v41, s[0:1] offset:224
.LBB0_61:
	s_waitcnt vmcnt(0)
	v_mul_f32_e32 v34, v0, v33
	v_mul_f32_e32 v35, v1, v33
	v_cvt_pk_bf16_f32 v34, v34, v35
	v_mul_f32_e32 v35, v2, v33
	v_mul_f32_e32 v33, v3, v33
	v_cvt_pk_bf16_f32 v35, v35, v33
	v_cndmask_b32_e64 v33, 0, 1, s[82:83]
	v_cmp_ne_u32_e64 s[0:1], 1, v33
	s_andn2_b64 vcc, exec, s[82:83]
	ds_write_b64 v46, v[34:35]
	s_cbranch_vccnz .LBB0_63
	s_ashr_i32 s79, s78, 31
	s_lshl_b64 s[34:35], s[78:79], 2
	s_add_u32 s34, s4, s34
	s_addc_u32 s35, s5, s35
	v_mov_b32_e32 v32, v101
.LBB0_63:
	s_waitcnt vmcnt(0)
	v_mul_f32_e32 v33, v4, v32
	v_mul_f32_e32 v34, v5, v32
	v_cvt_pk_bf16_f32 v34, v33, v34
	v_mul_f32_e32 v33, v6, v32
	v_mul_f32_e32 v32, v7, v32
	v_cvt_pk_bf16_f32 v35, v33, v32
	v_mov_b32_e32 v32, 1.0
	s_and_b64 vcc, exec, s[0:1]
	v_mov_b32_e32 v33, 1.0
	ds_write_b64 v46, v[34:35] offset:4352
	s_cbranch_vccnz .LBB0_65
	s_ashr_i32 s79, s78, 31
	s_lshl_b64 s[34:35], s[78:79], 2
	s_add_u32 s34, s4, s34
	s_addc_u32 s35, s5, s35
	v_mov_b32_e32 v33, v102
.LBB0_65:
	s_waitcnt vmcnt(0)
	v_mul_f32_e32 v34, v8, v33
	v_mul_f32_e32 v35, v9, v33
	v_cvt_pk_bf16_f32 v34, v34, v35
	v_mul_f32_e32 v35, v10, v33
	s_and_b64 vcc, exec, s[0:1]
	v_mul_f32_e32 v33, v11, v33
	v_cvt_pk_bf16_f32 v35, v35, v33
	ds_write_b64 v46, v[34:35] offset:8704
	s_cbranch_vccnz .LBB0_67
	s_ashr_i32 s79, s78, 31
	s_lshl_b64 s[34:35], s[78:79], 2
	s_add_u32 s34, s4, s34
	s_addc_u32 s35, s5, s35
	v_mov_b32_e32 v32, v103
.LBB0_67:
	s_waitcnt vmcnt(0)
	v_mul_f32_e32 v33, v12, v32
	v_mul_f32_e32 v34, v13, v32
	v_cvt_pk_bf16_f32 v34, v33, v34
	v_mul_f32_e32 v33, v14, v32
	v_mul_f32_e32 v32, v15, v32
	v_cvt_pk_bf16_f32 v35, v33, v32
	v_mov_b32_e32 v32, 1.0
	s_and_b64 vcc, exec, s[0:1]
	v_mov_b32_e32 v33, 1.0
	ds_write_b64 v46, v[34:35] offset:13056
	s_cbranch_vccnz .LBB0_69
	s_ashr_i32 s79, s78, 31
	s_lshl_b64 s[34:35], s[78:79], 2
	s_add_u32 s34, s4, s34
	s_addc_u32 s35, s5, s35
	v_mov_b32_e32 v33, v104
.LBB0_69:
	s_waitcnt vmcnt(0)
	v_mul_f32_e32 v34, v16, v33
	v_mul_f32_e32 v35, v17, v33
	v_cvt_pk_bf16_f32 v34, v34, v35
	v_mul_f32_e32 v35, v18, v33
	s_and_b64 vcc, exec, s[0:1]
	v_mul_f32_e32 v33, v19, v33
	v_cvt_pk_bf16_f32 v35, v35, v33
	ds_write_b64 v46, v[34:35] offset:17408
	s_cbranch_vccnz .LBB0_71
	s_ashr_i32 s79, s78, 31
	s_lshl_b64 s[34:35], s[78:79], 2
	s_add_u32 s34, s4, s34
	s_addc_u32 s35, s5, s35
	v_mov_b32_e32 v32, v105
.LBB0_71:
	s_waitcnt vmcnt(0)
	v_mul_f32_e32 v33, v20, v32
	v_mul_f32_e32 v34, v21, v32
	v_cvt_pk_bf16_f32 v34, v33, v34
	v_mul_f32_e32 v33, v22, v32
	v_mul_f32_e32 v32, v23, v32
	v_cvt_pk_bf16_f32 v35, v33, v32
	v_mov_b32_e32 v32, 1.0
	s_and_b64 vcc, exec, s[0:1]
	v_mov_b32_e32 v33, 1.0
	ds_write_b64 v46, v[34:35] offset:21760
	s_cbranch_vccnz .LBB0_73
	s_ashr_i32 s79, s78, 31
	s_lshl_b64 s[34:35], s[78:79], 2
	s_add_u32 s34, s4, s34
	s_addc_u32 s35, s5, s35
	v_mov_b32_e32 v33, v106
.LBB0_73:
	s_waitcnt vmcnt(0)
	v_mul_f32_e32 v34, v24, v33
	v_mul_f32_e32 v35, v25, v33
	v_cvt_pk_bf16_f32 v34, v34, v35
	v_mul_f32_e32 v35, v26, v33
	s_and_b64 vcc, exec, s[0:1]
	v_mul_f32_e32 v33, v27, v33
	v_cvt_pk_bf16_f32 v35, v35, v33
	ds_write_b64 v46, v[34:35] offset:26112
	s_cbranch_vccnz .LBB0_75
	s_ashr_i32 s79, s78, 31
	s_lshl_b64 s[0:1], s[78:79], 2
	s_add_u32 s0, s4, s0
	s_addc_u32 s1, s5, s1
	v_mov_b32_e32 v32, v107

.LBB0_300:
	s_lshr_b32 s72, s19, 8
	v_cvt_f32_u32_e32 v32, s72
	s_sub_i32 s34, 0, s72
	s_abs_i32 s1, s55
	s_ashr_i32 s0, s55, 31
	v_rcp_iflag_f32_e32 v32, v32
	v_mov_b32_e32 v33, 1.0
	s_barrier
	v_mul_f32_e32 v32, 0x4f7ffffe, v32
	v_cvt_u32_f32_e32 v32, v32
	s_nop 0
	v_readfirstlane_b32 s35, v32
	s_mul_i32 s34, s34, s35
	s_mul_hi_u32 s34, s35, s34
	s_add_i32 s35, s35, s34
	s_mul_hi_u32 s34, s1, s35
	s_mul_i32 s35, s34, s72
	s_sub_i32 s1, s1, s35
	s_add_i32 s54, s34, 1
	s_sub_i32 s35, s1, s72
	s_cmp_ge_u32 s1, s72
	s_cselect_b32 s34, s54, s34
	s_cselect_b32 s1, s35, s1
	s_add_i32 s35, s34, 1
	s_cmp_ge_u32 s1, s72
	s_cselect_b32 s1, s35, s34
	s_xor_b32 s1, s1, s0
	s_sub_i32 s73, s1, s0
	s_lshl_b32 s54, s73, 6
	s_cmp_lg_u64 s[4:5], 0
	s_cselect_b64 s[60:61], -1, 0
	s_add_i32 s58, s54, s49
	s_cmp_eq_u64 s[4:5], 0
	v_mov_b32_e32 v32, 1.0
	s_cbranch_scc1 .LBB0_302
	s_ashr_i32 s59, s58, 31
	s_lshl_b64 s[0:1], s[58:59], 2
	s_add_u32 s0, s4, s0
	s_addc_u32 s1, s5, s1
	global_load_dword v33, v41, s[0:1]
	global_load_dword v101, v41, s[0:1] offset:32
	global_load_dword v102, v41, s[0:1] offset:64
	global_load_dword v103, v41, s[0:1] offset:96
	global_load_dword v104, v41, s[0:1] offset:128
	global_load_dword v105, v41, s[0:1] offset:160
	global_load_dword v106, v41, s[0:1] offset:192
	global_load_dword v107, v41, s[0:1] offset:224
.LBB0_302:
	s_waitcnt vmcnt(0)
	v_mul_f32_e32 v34, v0, v33
	v_mul_f32_e32 v35, v1, v33
	v_cvt_pk_bf16_f32 v34, v34, v35
	v_mul_f32_e32 v35, v2, v33
	v_mul_f32_e32 v33, v3, v33
	v_cvt_pk_bf16_f32 v35, v35, v33
	v_cndmask_b32_e64 v33, 0, 1, s[60:61]
	v_cmp_ne_u32_e64 s[0:1], 1, v33
	s_andn2_b64 vcc, exec, s[60:61]
	ds_write_b64 v45, v[34:35]
	s_cbranch_vccnz .LBB0_304
	s_ashr_i32 s59, s58, 31
	s_lshl_b64 s[34:35], s[58:59], 2
	s_add_u32 s34, s4, s34
	s_addc_u32 s35, s5, s35
	v_mov_b32_e32 v32, v101
.LBB0_304:
	s_waitcnt vmcnt(0)
	v_mul_f32_e32 v33, v4, v32
	v_mul_f32_e32 v34, v5, v32
	v_cvt_pk_bf16_f32 v34, v33, v34
	v_mul_f32_e32 v33, v6, v32
	v_mul_f32_e32 v32, v7, v32
	v_cvt_pk_bf16_f32 v35, v33, v32
	v_mov_b32_e32 v32, 1.0
	s_and_b64 vcc, exec, s[0:1]
	v_mov_b32_e32 v33, 1.0
	ds_write_b64 v45, v[34:35] offset:4352
	s_cbranch_vccnz .LBB0_306
	s_ashr_i32 s59, s58, 31
	s_lshl_b64 s[34:35], s[58:59], 2
	s_add_u32 s34, s4, s34
	s_addc_u32 s35, s5, s35
	v_mov_b32_e32 v33, v102
.LBB0_306:
	s_waitcnt vmcnt(0)
	v_mul_f32_e32 v34, v8, v33
	v_mul_f32_e32 v35, v9, v33
	v_cvt_pk_bf16_f32 v34, v34, v35
	v_mul_f32_e32 v35, v10, v33
	s_and_b64 vcc, exec, s[0:1]
	v_mul_f32_e32 v33, v11, v33
	v_cvt_pk_bf16_f32 v35, v35, v33
	ds_write_b64 v45, v[34:35] offset:8704
	s_cbranch_vccnz .LBB0_308
	s_ashr_i32 s59, s58, 31
	s_lshl_b64 s[34:35], s[58:59], 2
	s_add_u32 s34, s4, s34
	s_addc_u32 s35, s5, s35
	v_mov_b32_e32 v32, v103
.LBB0_308:
	s_waitcnt vmcnt(0)
	v_mul_f32_e32 v33, v12, v32
	v_mul_f32_e32 v34, v13, v32
	v_cvt_pk_bf16_f32 v34, v33, v34
	v_mul_f32_e32 v33, v14, v32
	v_mul_f32_e32 v32, v15, v32
	v_cvt_pk_bf16_f32 v35, v33, v32
	v_mov_b32_e32 v32, 1.0
	s_and_b64 vcc, exec, s[0:1]
	v_mov_b32_e32 v33, 1.0
	ds_write_b64 v45, v[34:35] offset:13056
	s_cbranch_vccnz .LBB0_310
	s_ashr_i32 s59, s58, 31
	s_lshl_b64 s[34:35], s[58:59], 2
	s_add_u32 s34, s4, s34
	s_addc_u32 s35, s5, s35
	v_mov_b32_e32 v33, v104
.LBB0_310:
	s_waitcnt vmcnt(0)
	v_mul_f32_e32 v34, v16, v33
	v_mul_f32_e32 v35, v17, v33
	v_cvt_pk_bf16_f32 v34, v34, v35
	v_mul_f32_e32 v35, v18, v33
	s_and_b64 vcc, exec, s[0:1]
	v_mul_f32_e32 v33, v19, v33
	v_cvt_pk_bf16_f32 v35, v35, v33
	ds_write_b64 v45, v[34:35] offset:17408
	s_cbranch_vccnz .LBB0_312
	s_ashr_i32 s59, s58, 31
	s_lshl_b64 s[34:35], s[58:59], 2
	s_add_u32 s34, s4, s34
	s_addc_u32 s35, s5, s35
	v_mov_b32_e32 v32, v105
.LBB0_312:
	s_waitcnt vmcnt(0)
	v_mul_f32_e32 v33, v20, v32
	v_mul_f32_e32 v34, v21, v32
	v_cvt_pk_bf16_f32 v34, v33, v34
	v_mul_f32_e32 v33, v22, v32
	v_mul_f32_e32 v32, v23, v32
	v_cvt_pk_bf16_f32 v35, v33, v32
	v_mov_b32_e32 v32, 1.0
	s_and_b64 vcc, exec, s[0:1]
	v_mov_b32_e32 v33, 1.0
	ds_write_b64 v45, v[34:35] offset:21760
	s_cbranch_vccnz .LBB0_314
	s_ashr_i32 s59, s58, 31
	s_lshl_b64 s[34:35], s[58:59], 2
	s_add_u32 s34, s4, s34
	s_addc_u32 s35, s5, s35
	v_mov_b32_e32 v33, v106
.LBB0_314:
	s_waitcnt vmcnt(0)
	v_mul_f32_e32 v34, v24, v33
	v_mul_f32_e32 v35, v25, v33
	v_cvt_pk_bf16_f32 v34, v34, v35
	v_mul_f32_e32 v35, v26, v33
	s_and_b64 vcc, exec, s[0:1]
	v_mul_f32_e32 v33, v27, v33
	v_cvt_pk_bf16_f32 v35, v35, v33
	ds_write_b64 v45, v[34:35] offset:26112
	s_cbranch_vccnz .LBB0_316
	s_ashr_i32 s59, s58, 31
	s_lshl_b64 s[0:1], s[58:59], 2
	s_add_u32 s0, s4, s0
	s_addc_u32 s1, s5, s1
	v_mov_b32_e32 v32, v107

.LBB0_1083:
	v_lshlrev_b64 v[104:105], 10, v[160:161]
	v_or3_b32 v104, v104, v146, s42
	v_lshlrev_b64 v[104:105], 1, v[104:105]
	v_lshl_add_u64 v[104:105], s[40:41], 0, v[104:105]
	global_load_dwordx2 v[106:107], v[104:105], off
	global_load_dwordx2 v[108:109], v[104:105], off offset:32
	global_load_dwordx2 v[110:111], v[104:105], off offset:64
	global_load_dwordx2 v[112:113], v[104:105], off offset:96
	global_load_dwordx2 v[114:115], v[104:105], off offset:128
	global_load_dwordx2 v[116:117], v[104:105], off offset:160
	global_load_dwordx2 v[118:119], v[104:105], off offset:192
	global_load_dwordx2 v[120:121], v[104:105], off offset:224
	global_load_dwordx2 v[122:123], v[104:105], off offset:256
	global_load_dwordx2 v[124:125], v[104:105], off offset:288
	global_load_dwordx2 v[126:127], v[104:105], off offset:320
	global_load_dwordx2 v[128:129], v[104:105], off offset:352
	global_load_dwordx2 v[130:131], v[104:105], off offset:384
	global_load_dwordx2 v[162:163], v[104:105], off offset:416
	global_load_dwordx2 v[164:165], v[104:105], off offset:448
	global_load_dwordx2 v[166:167], v[104:105], off offset:480
	v_pk_mul_f32 v[0:1], v[102:103], v[102:103]
	v_pk_mul_f32 v[2:3], v[100:101], v[100:101]
	v_mul_f32_e32 v10, v72, v72
	v_pk_mov_b32 v[4:5], v[2:3], v[0:1] op_sel:[1,0]
	v_mov_b32_e32 v3, v1
	v_pk_add_f32 v[0:1], v[4:5], v[2:3]
	v_pk_mul_f32 v[2:3], v[98:99], v[98:99]
	v_pk_mul_f32 v[4:5], v[96:97], v[96:97]
	v_pk_add_f32 v[0:1], v[0:1], v[0:1] op_sel:[0,1] op_sel_hi:[1,0]
	v_pk_mov_b32 v[6:7], v[4:5], v[2:3] op_sel:[1,0]
	v_mov_b32_e32 v5, v3
	v_pk_add_f32 v[2:3], v[6:7], v[4:5]
	v_mul_f32_e32 v4, v48, v48
	v_mul_f32_e32 v5, v49, v49
	v_pk_add_f32 v[2:3], v[2:3], v[2:3] op_sel:[0,1] op_sel_hi:[1,0]
	v_mov_b32_e32 v1, v4
	v_mov_b32_e32 v3, v5
	v_pk_add_f32 v[0:1], v[0:1], v[2:3]
	v_mul_f32_e32 v2, v53, v53
	v_mul_f32_e32 v4, v55, v55
	v_mul_f32_e32 v6, v50, v50
	v_mul_f32_e32 v7, v51, v51
	v_pk_fma_f32 v[2:3], v[52:53], v[52:53], v[2:3] op_sel_hi:[1,1,0]
	v_pk_fma_f32 v[4:5], v[54:55], v[54:55], v[4:5] op_sel_hi:[1,1,0]
	v_mov_b32_e32 v3, v6
	v_mov_b32_e32 v5, v7
	v_pk_add_f32 v[2:3], v[2:3], v[4:5]
	v_pk_mul_f32 v[4:5], v[92:93], v[92:93]
	v_pk_add_f32 v[0:1], v[0:1], v[2:3]
	v_pk_mul_f32 v[2:3], v[94:95], v[94:95]
	v_pk_add_f32 v[0:1], v[0:1], v[0:1] op_sel:[0,1] op_sel_hi:[1,0]
	v_pk_mov_b32 v[6:7], v[4:5], v[2:3] op_sel:[1,0]
	v_mov_b32_e32 v5, v3
	v_pk_add_f32 v[2:3], v[6:7], v[4:5]
	v_mul_f32_e32 v4, v84, v84
	v_mul_f32_e32 v5, v85, v85
	v_pk_add_f32 v[2:3], v[2:3], v[2:3] op_sel:[0,1] op_sel_hi:[1,0]
	v_mov_b32_e32 v1, v4
	v_mov_b32_e32 v3, v5
	v_pk_add_f32 v[0:1], v[0:1], v[2:3]
	v_mul_f32_e32 v2, v89, v89
	v_mul_f32_e32 v4, v91, v91
	v_mul_f32_e32 v6, v86, v86
	v_mul_f32_e32 v7, v87, v87
	v_pk_fma_f32 v[2:3], v[88:89], v[88:89], v[2:3] op_sel_hi:[1,1,0]
	v_pk_fma_f32 v[4:5], v[90:91], v[90:91], v[4:5] op_sel_hi:[1,1,0]
	v_mov_b32_e32 v3, v6
	v_mov_b32_e32 v5, v7
	v_pk_add_f32 v[2:3], v[2:3], v[4:5]
	v_pk_mul_f32 v[4:5], v[80:81], v[80:81]
	v_pk_add_f32 v[2:3], v[0:1], v[2:3]
	v_pk_mul_f32 v[0:1], v[82:83], v[82:83]
	v_mul_f32_e32 v11, v73, v73
	v_pk_mov_b32 v[6:7], v[4:5], v[0:1] op_sel:[1,0]
	v_mov_b32_e32 v5, v1
	v_lshlrev_b64 v[0:1], 10, v[160:161]
	v_or3_b32 v1, v1, 0, 0
	v_or3_b32 v0, v0, v146, s42
	v_pk_add_f32 v[4:5], v[6:7], v[4:5]
	v_lshlrev_b64 v[6:7], 1, v[0:1]
	v_lshl_add_u64 v[0:1], s[40:41], 0, v[6:7]
	v_pk_add_f32 v[2:3], v[2:3], v[2:3] op_sel:[0,1] op_sel_hi:[1,0]
	v_pk_add_f32 v[4:5], v[4:5], v[4:5] op_sel:[0,1] op_sel_hi:[1,0]
	v_mov_b32_e32 v3, v10
	v_mov_b32_e32 v5, v11
	v_pk_add_f32 v[2:3], v[2:3], v[4:5]
	v_mul_f32_e32 v4, v77, v77
	v_mul_f32_e32 v10, v79, v79
	v_mul_f32_e32 v12, v74, v74
	v_mul_f32_e32 v13, v75, v75
	v_pk_fma_f32 v[4:5], v[76:77], v[76:77], v[4:5] op_sel_hi:[1,1,0]
	v_pk_fma_f32 v[10:11], v[78:79], v[78:79], v[10:11] op_sel_hi:[1,1,0]
	v_mov_b32_e32 v5, v12
	v_mov_b32_e32 v11, v13
	v_pk_add_f32 v[4:5], v[4:5], v[10:11]
	v_pk_mul_f32 v[10:11], v[68:69], v[68:69]
	v_pk_add_f32 v[2:3], v[2:3], v[4:5]
	v_pk_mul_f32 v[4:5], v[70:71], v[70:71]
	v_pk_add_f32 v[2:3], v[2:3], v[2:3] op_sel:[0,1] op_sel_hi:[1,0]
	v_pk_mov_b32 v[12:13], v[10:11], v[4:5] op_sel:[1,0]
	v_mov_b32_e32 v11, v5
	v_pk_add_f32 v[4:5], v[12:13], v[10:11]
	v_mul_f32_e32 v10, v44, v44
	v_mul_f32_e32 v11, v45, v45
	v_pk_add_f32 v[4:5], v[4:5], v[4:5] op_sel:[0,1] op_sel_hi:[1,0]
	v_mov_b32_e32 v3, v10
	v_mov_b32_e32 v5, v11
	v_pk_add_f32 v[2:3], v[2:3], v[4:5]
	v_mul_f32_e32 v4, v65, v65
	v_mul_f32_e32 v10, v67, v67
	v_mul_f32_e32 v12, v46, v46
	v_mul_f32_e32 v13, v47, v47
	v_pk_fma_f32 v[4:5], v[64:65], v[64:65], v[4:5] op_sel_hi:[1,1,0]
	v_pk_fma_f32 v[10:11], v[66:67], v[66:67], v[10:11] op_sel_hi:[1,1,0]
	v_mov_b32_e32 v5, v12
	v_mov_b32_e32 v11, v13
	v_pk_add_f32 v[4:5], v[4:5], v[10:11]
	v_pk_mul_f32 v[10:11], v[40:41], v[40:41]
	v_pk_add_f32 v[2:3], v[2:3], v[4:5]
	v_pk_mul_f32 v[4:5], v[42:43], v[42:43]
	v_pk_add_f32 v[2:3], v[2:3], v[2:3] op_sel:[0,1] op_sel_hi:[1,0]
	v_pk_mov_b32 v[12:13], v[10:11], v[4:5] op_sel:[1,0]
	v_mov_b32_e32 v11, v5
	v_pk_add_f32 v[4:5], v[12:13], v[10:11]
	v_mul_f32_e32 v10, v32, v32
	v_mul_f32_e32 v11, v33, v33
	v_pk_add_f32 v[4:5], v[4:5], v[4:5] op_sel:[0,1] op_sel_hi:[1,0]
	v_mov_b32_e32 v3, v10
	v_mov_b32_e32 v5, v11
	v_pk_add_f32 v[2:3], v[2:3], v[4:5]
	v_mul_f32_e32 v4, v37, v37
	v_mul_f32_e32 v10, v39, v39
	v_mul_f32_e32 v12, v34, v34
	v_mul_f32_e32 v13, v35, v35
	v_pk_fma_f32 v[4:5], v[36:37], v[36:37], v[4:5] op_sel_hi:[1,1,0]
	v_pk_fma_f32 v[10:11], v[38:39], v[38:39], v[10:11] op_sel_hi:[1,1,0]
	v_mov_b32_e32 v5, v12
	v_mov_b32_e32 v11, v13
	v_pk_add_f32 v[4:5], v[4:5], v[10:11]
	s_add_i32 s69, s69, s70
	v_pk_add_f32 v[2:3], v[2:3], v[4:5]
	v_and_b32_e32 v4, 64, v222
	v_add_f32_e32 v2, v2, v3
	v_xor_b32_e32 v3, 16, v222
	v_add_u32_e32 v4, 64, v4
	v_cmp_lt_i32_e32 vcc, v3, v4
	s_add_i32 s73, s73, s33
	s_nop 0
	v_cndmask_b32_e32 v3, v222, v3, vcc
	v_lshlrev_b32_e32 v3, 2, v3
	ds_bpermute_b32 v3, v3, v2
	s_waitcnt lgkmcnt(0)
	v_add_f32_e32 v2, v2, v3
	v_xor_b32_e32 v3, 32, v222
	v_cmp_lt_i32_e32 vcc, v3, v4
	s_nop 1
	v_cndmask_b32_e32 v3, v222, v3, vcc
	v_lshlrev_b32_e32 v3, 2, v3
	ds_bpermute_b32 v4, v3, v2
	s_waitcnt vmcnt(15)
	v_mov_b64_e32 v[8:9], v[106:107]
	v_lshlrev_b32_e32 v3, 16, v8
	v_mul_f32_e32 v5, 0xbfb8aa3b, v3
	v_exp_f32_e32 v5, v5
	s_and_b64 vcc, exec, s[6:7]
	s_waitcnt lgkmcnt(0)
	v_add_f32_e32 v2, v2, v4
	v_fmamk_f32 v2, v2, 0x3b800000, v223
	v_add_f32_e32 v4, 1.0, v5
	v_rsq_f32_e32 v2, v2
	v_rcp_f32_e32 v5, v4
	v_mov_b32_e32 v4, v100
	v_pk_mul_f32 v[10:11], v[4:5], v[2:3]
	v_and_b32_e32 v3, 0xffff0000, v8
	v_mul_f32_e32 v4, 0xbfb8aa3b, v3
	v_exp_f32_e32 v4, v4
	s_nop 0
	v_add_f32_e32 v4, 1.0, v4
	v_rcp_f32_e32 v5, v4
	v_mov_b32_e32 v4, v101
	v_pk_mul_f32 v[12:13], v[4:5], v[2:3]
	v_lshlrev_b32_e32 v3, 16, v9
	v_mul_f32_e32 v4, 0xbfb8aa3b, v3
	v_exp_f32_e32 v4, v4
	s_nop 0
	v_add_f32_e32 v4, 1.0, v4
	v_rcp_f32_e32 v5, v4
	v_mov_b32_e32 v4, v102
	v_pk_mul_f32 v[14:15], v[4:5], v[2:3]
	v_and_b32_e32 v3, 0xffff0000, v9
	v_mul_f32_e32 v4, 0xbfb8aa3b, v3
	v_exp_f32_e32 v8, v4
	v_lshl_add_u64 v[4:5], s[26:27], 0, v[6:7]
	v_mul_f32_e32 v6, v10, v11
	v_mul_f32_e32 v9, v12, v13
	v_add_f32_e32 v7, 1.0, v8
	v_rcp_f32_e32 v7, v7
	v_cvt_pk_bf16_f32 v8, v6, v9
	v_mov_b32_e32 v6, v103
	v_mul_f32_e32 v9, v14, v15
	v_pk_mul_f32 v[6:7], v[6:7], v[2:3]
	v_mov_b32_e32 v10, v97
	v_mul_f32_e32 v3, v6, v7
	v_cvt_pk_bf16_f32 v9, v9, v3
	global_store_dwordx2 v[4:5], v[8:9], off
	v_mov_b32_e32 v12, v98
	s_waitcnt vmcnt(15)
	v_mov_b64_e32 v[6:7], v[108:109]
	v_lshlrev_b32_e32 v3, 16, v6
	v_mul_f32_e32 v8, 0xbfb8aa3b, v3
	v_exp_f32_e32 v8, v8
	s_nop 0
	v_add_f32_e32 v8, 1.0, v8
	v_rcp_f32_e32 v9, v8
	v_mov_b32_e32 v8, v96
	v_pk_mul_f32 v[8:9], v[8:9], v[2:3]
	v_and_b32_e32 v3, 0xffff0000, v6
	v_mul_f32_e32 v6, 0xbfb8aa3b, v3
	v_exp_f32_e32 v6, v6
	v_mul_f32_e32 v8, v8, v9
	v_add_f32_e32 v6, 1.0, v6
	v_rcp_f32_e32 v11, v6
	s_nop 0
	v_pk_mul_f32 v[10:11], v[10:11], v[2:3]
	v_lshlrev_b32_e32 v3, 16, v7
	v_mul_f32_e32 v6, 0xbfb8aa3b, v3
	v_exp_f32_e32 v6, v6
	v_mul_f32_e32 v9, v10, v11
	v_cvt_pk_bf16_f32 v8, v8, v9
	v_mov_b32_e32 v10, v53
	v_add_f32_e32 v6, 1.0, v6
	v_rcp_f32_e32 v13, v6
	s_nop 0
	v_pk_mul_f32 v[12:13], v[12:13], v[2:3]
	v_and_b32_e32 v3, 0xffff0000, v7
	v_mul_f32_e32 v6, 0xbfb8aa3b, v3
	v_exp_f32_e32 v7, v6
	v_mov_b32_e32 v6, v99
	v_mul_f32_e32 v9, v12, v13
	v_mov_b32_e32 v12, v54
	v_add_f32_e32 v7, 1.0, v7
	v_rcp_f32_e32 v7, v7
	s_nop 0
	v_pk_mul_f32 v[6:7], v[6:7], v[2:3]
	s_nop 0
	v_mul_f32_e32 v3, v6, v7
	v_cvt_pk_bf16_f32 v9, v9, v3
	global_store_dwordx2 v[4:5], v[8:9], off offset:32
	s_waitcnt vmcnt(15)
	v_mov_b64_e32 v[6:7], v[110:111]
	v_lshlrev_b32_e32 v3, 16, v6
	v_mul_f32_e32 v8, 0xbfb8aa3b, v3
	v_exp_f32_e32 v8, v8
	s_nop 0
	v_add_f32_e32 v8, 1.0, v8
	v_rcp_f32_e32 v9, v8
	v_mov_b32_e32 v8, v52
	v_pk_mul_f32 v[8:9], v[8:9], v[2:3]
	v_and_b32_e32 v3, 0xffff0000, v6
	v_mul_f32_e32 v6, 0xbfb8aa3b, v3
	v_exp_f32_e32 v6, v6
	v_mul_f32_e32 v8, v8, v9
	v_add_f32_e32 v6, 1.0, v6
	v_rcp_f32_e32 v11, v6
	s_nop 0
	v_pk_mul_f32 v[10:11], v[10:11], v[2:3]
	v_lshlrev_b32_e32 v3, 16, v7
	v_mul_f32_e32 v6, 0xbfb8aa3b, v3
	v_exp_f32_e32 v6, v6
	v_mul_f32_e32 v9, v10, v11
	v_cvt_pk_bf16_f32 v8, v8, v9
	v_mov_b32_e32 v10, v49
	v_add_f32_e32 v6, 1.0, v6
	v_rcp_f32_e32 v13, v6
	s_nop 0
	v_pk_mul_f32 v[12:13], v[12:13], v[2:3]
	v_and_b32_e32 v3, 0xffff0000, v7
	v_mul_f32_e32 v6, 0xbfb8aa3b, v3
	v_exp_f32_e32 v7, v6
	v_mov_b32_e32 v6, v55
	v_mul_f32_e32 v9, v12, v13
	v_mov_b32_e32 v12, v50
	v_add_f32_e32 v7, 1.0, v7
	v_rcp_f32_e32 v7, v7
	s_nop 0
	v_pk_mul_f32 v[6:7], v[6:7], v[2:3]
	s_nop 0
	v_mul_f32_e32 v3, v6, v7
	v_cvt_pk_bf16_f32 v9, v9, v3
	global_store_dwordx2 v[4:5], v[8:9], off offset:64
	s_waitcnt vmcnt(15)
	v_mov_b64_e32 v[6:7], v[112:113]
	v_lshlrev_b32_e32 v3, 16, v6
	v_mul_f32_e32 v8, 0xbfb8aa3b, v3
	v_exp_f32_e32 v8, v8
	s_nop 0
	v_add_f32_e32 v8, 1.0, v8
	v_rcp_f32_e32 v9, v8
	v_mov_b32_e32 v8, v48
	v_pk_mul_f32 v[8:9], v[8:9], v[2:3]
	v_and_b32_e32 v3, 0xffff0000, v6
	v_mul_f32_e32 v6, 0xbfb8aa3b, v3
	v_exp_f32_e32 v6, v6
	v_mul_f32_e32 v8, v8, v9
	v_add_f32_e32 v6, 1.0, v6
	v_rcp_f32_e32 v11, v6
	s_nop 0
	v_pk_mul_f32 v[10:11], v[10:11], v[2:3]
	v_lshlrev_b32_e32 v3, 16, v7
	v_mul_f32_e32 v6, 0xbfb8aa3b, v3
	v_exp_f32_e32 v6, v6
	v_mul_f32_e32 v9, v10, v11
	v_cvt_pk_bf16_f32 v8, v8, v9
	v_mov_b32_e32 v10, v93
	v_add_f32_e32 v6, 1.0, v6
	v_rcp_f32_e32 v13, v6
	s_nop 0
	v_pk_mul_f32 v[12:13], v[12:13], v[2:3]
	v_and_b32_e32 v3, 0xffff0000, v7
	v_mul_f32_e32 v6, 0xbfb8aa3b, v3
	v_exp_f32_e32 v7, v6
	v_mov_b32_e32 v6, v51
	v_mul_f32_e32 v9, v12, v13
	v_mov_b32_e32 v12, v94
	v_add_f32_e32 v7, 1.0, v7
	v_rcp_f32_e32 v7, v7
	s_nop 0
	v_pk_mul_f32 v[6:7], v[6:7], v[2:3]
	s_nop 0
	v_mul_f32_e32 v3, v6, v7
	v_cvt_pk_bf16_f32 v9, v9, v3
	global_store_dwordx2 v[4:5], v[8:9], off offset:96
	s_waitcnt vmcnt(15)
	v_mov_b64_e32 v[6:7], v[114:115]
	v_lshlrev_b32_e32 v3, 16, v6
	v_mul_f32_e32 v8, 0xbfb8aa3b, v3
	v_exp_f32_e32 v8, v8
	s_nop 0
	v_add_f32_e32 v8, 1.0, v8
	v_rcp_f32_e32 v9, v8
	v_mov_b32_e32 v8, v92
	v_pk_mul_f32 v[8:9], v[8:9], v[2:3]
	v_and_b32_e32 v3, 0xffff0000, v6
	v_mul_f32_e32 v6, 0xbfb8aa3b, v3
	v_exp_f32_e32 v6, v6
	v_mul_f32_e32 v8, v8, v9
	v_add_f32_e32 v6, 1.0, v6
	v_rcp_f32_e32 v11, v6
	s_nop 0
	v_pk_mul_f32 v[10:11], v[10:11], v[2:3]
	v_lshlrev_b32_e32 v3, 16, v7
	v_mul_f32_e32 v6, 0xbfb8aa3b, v3
	v_exp_f32_e32 v6, v6
	v_mul_f32_e32 v9, v10, v11
	v_cvt_pk_bf16_f32 v8, v8, v9
	v_mov_b32_e32 v10, v89
	v_add_f32_e32 v6, 1.0, v6
	v_rcp_f32_e32 v13, v6
	s_nop 0
	v_pk_mul_f32 v[12:13], v[12:13], v[2:3]
	v_and_b32_e32 v3, 0xffff0000, v7
	v_mul_f32_e32 v6, 0xbfb8aa3b, v3
	v_exp_f32_e32 v7, v6
	v_mov_b32_e32 v6, v95
	v_mul_f32_e32 v9, v12, v13
	v_mov_b32_e32 v12, v90
	v_add_f32_e32 v7, 1.0, v7
	v_rcp_f32_e32 v7, v7
	s_nop 0
	v_pk_mul_f32 v[6:7], v[6:7], v[2:3]
	s_nop 0
	v_mul_f32_e32 v3, v6, v7
	v_cvt_pk_bf16_f32 v9, v9, v3
	global_store_dwordx2 v[4:5], v[8:9], off offset:128
	s_waitcnt vmcnt(15)
	v_mov_b64_e32 v[6:7], v[116:117]
	v_lshlrev_b32_e32 v3, 16, v6
	v_mul_f32_e32 v8, 0xbfb8aa3b, v3
	v_exp_f32_e32 v8, v8
	s_nop 0
	v_add_f32_e32 v8, 1.0, v8
	v_rcp_f32_e32 v9, v8
	v_mov_b32_e32 v8, v88
	v_pk_mul_f32 v[8:9], v[8:9], v[2:3]
	v_and_b32_e32 v3, 0xffff0000, v6
	v_mul_f32_e32 v6, 0xbfb8aa3b, v3
	v_exp_f32_e32 v6, v6
	v_mul_f32_e32 v8, v8, v9
	v_add_f32_e32 v6, 1.0, v6
	v_rcp_f32_e32 v11, v6
	s_nop 0
	v_pk_mul_f32 v[10:11], v[10:11], v[2:3]
	v_lshlrev_b32_e32 v3, 16, v7
	v_mul_f32_e32 v6, 0xbfb8aa3b, v3
	v_exp_f32_e32 v6, v6
	v_mul_f32_e32 v9, v10, v11
	v_cvt_pk_bf16_f32 v8, v8, v9
	v_mov_b32_e32 v10, v85
	v_add_f32_e32 v6, 1.0, v6
	v_rcp_f32_e32 v13, v6
	s_nop 0
	v_pk_mul_f32 v[12:13], v[12:13], v[2:3]
	v_and_b32_e32 v3, 0xffff0000, v7
	v_mul_f32_e32 v6, 0xbfb8aa3b, v3
	v_exp_f32_e32 v7, v6
	v_mov_b32_e32 v6, v91
	v_mul_f32_e32 v9, v12, v13
	v_mov_b32_e32 v12, v86
	v_add_f32_e32 v7, 1.0, v7
	v_rcp_f32_e32 v7, v7
	s_nop 0
	v_pk_mul_f32 v[6:7], v[6:7], v[2:3]
	s_nop 0
	v_mul_f32_e32 v3, v6, v7
	v_cvt_pk_bf16_f32 v9, v9, v3
	global_store_dwordx2 v[4:5], v[8:9], off offset:160
	s_waitcnt vmcnt(15)
	v_mov_b64_e32 v[6:7], v[118:119]
	v_lshlrev_b32_e32 v3, 16, v6
	v_mul_f32_e32 v8, 0xbfb8aa3b, v3
	v_exp_f32_e32 v8, v8
	s_nop 0
	v_add_f32_e32 v8, 1.0, v8
	v_rcp_f32_e32 v9, v8
	v_mov_b32_e32 v8, v84
	v_pk_mul_f32 v[8:9], v[8:9], v[2:3]
	v_and_b32_e32 v3, 0xffff0000, v6
	v_mul_f32_e32 v6, 0xbfb8aa3b, v3
	v_exp_f32_e32 v6, v6
	v_mul_f32_e32 v8, v8, v9
	v_add_f32_e32 v6, 1.0, v6
	v_rcp_f32_e32 v11, v6
	s_nop 0
	v_pk_mul_f32 v[10:11], v[10:11], v[2:3]
	v_lshlrev_b32_e32 v3, 16, v7
	v_mul_f32_e32 v6, 0xbfb8aa3b, v3
	v_exp_f32_e32 v6, v6
	v_mul_f32_e32 v9, v10, v11
	v_cvt_pk_bf16_f32 v8, v8, v9
	v_mov_b32_e32 v10, v81
	v_add_f32_e32 v6, 1.0, v6
	v_rcp_f32_e32 v13, v6
	s_nop 0
	v_pk_mul_f32 v[12:13], v[12:13], v[2:3]
	v_and_b32_e32 v3, 0xffff0000, v7
	v_mul_f32_e32 v6, 0xbfb8aa3b, v3
	v_exp_f32_e32 v7, v6
	v_mov_b32_e32 v6, v87
	v_mul_f32_e32 v9, v12, v13
	v_mov_b32_e32 v12, v82
	v_add_f32_e32 v7, 1.0, v7
	v_rcp_f32_e32 v7, v7
	s_nop 0
	v_pk_mul_f32 v[6:7], v[6:7], v[2:3]
	s_nop 0
	v_mul_f32_e32 v3, v6, v7
	v_cvt_pk_bf16_f32 v9, v9, v3
	global_store_dwordx2 v[4:5], v[8:9], off offset:192
	s_waitcnt vmcnt(15)
	v_mov_b64_e32 v[6:7], v[120:121]
	v_lshlrev_b32_e32 v3, 16, v6
	v_mul_f32_e32 v8, 0xbfb8aa3b, v3
	v_exp_f32_e32 v8, v8
	s_nop 0
	v_add_f32_e32 v8, 1.0, v8
	v_rcp_f32_e32 v9, v8
	v_mov_b32_e32 v8, v80
	v_pk_mul_f32 v[8:9], v[8:9], v[2:3]
	v_and_b32_e32 v3, 0xffff0000, v6
	v_mul_f32_e32 v6, 0xbfb8aa3b, v3
	v_exp_f32_e32 v6, v6
	v_mul_f32_e32 v8, v8, v9
	v_add_f32_e32 v6, 1.0, v6
	v_rcp_f32_e32 v11, v6
	s_nop 0
	v_pk_mul_f32 v[10:11], v[10:11], v[2:3]
	v_lshlrev_b32_e32 v3, 16, v7
	v_mul_f32_e32 v6, 0xbfb8aa3b, v3
	v_exp_f32_e32 v6, v6
	v_mul_f32_e32 v9, v10, v11
	v_cvt_pk_bf16_f32 v8, v8, v9
	v_mov_b32_e32 v10, v77
	v_add_f32_e32 v6, 1.0, v6
	v_rcp_f32_e32 v13, v6
	s_nop 0
	v_pk_mul_f32 v[12:13], v[12:13], v[2:3]
	v_and_b32_e32 v3, 0xffff0000, v7
	v_mul_f32_e32 v6, 0xbfb8aa3b, v3
	v_exp_f32_e32 v7, v6
	v_mov_b32_e32 v6, v83
	v_mul_f32_e32 v9, v12, v13
	v_mov_b32_e32 v12, v78
	v_add_f32_e32 v7, 1.0, v7
	v_rcp_f32_e32 v7, v7
	s_nop 0
	v_pk_mul_f32 v[6:7], v[6:7], v[2:3]
	s_nop 0
	v_mul_f32_e32 v3, v6, v7
	v_cvt_pk_bf16_f32 v9, v9, v3
	global_store_dwordx2 v[4:5], v[8:9], off offset:224
	s_waitcnt vmcnt(15)
	v_mov_b64_e32 v[6:7], v[122:123]
	v_lshlrev_b32_e32 v3, 16, v6
	v_mul_f32_e32 v8, 0xbfb8aa3b, v3
	v_exp_f32_e32 v8, v8
	s_nop 0
	v_add_f32_e32 v8, 1.0, v8
	v_rcp_f32_e32 v9, v8
	v_mov_b32_e32 v8, v76
	v_pk_mul_f32 v[8:9], v[8:9], v[2:3]
	v_and_b32_e32 v3, 0xffff0000, v6
	v_mul_f32_e32 v6, 0xbfb8aa3b, v3
	v_exp_f32_e32 v6, v6
	v_mul_f32_e32 v8, v8, v9
	v_add_f32_e32 v6, 1.0, v6
	v_rcp_f32_e32 v11, v6
	s_nop 0
	v_pk_mul_f32 v[10:11], v[10:11], v[2:3]
	v_lshlrev_b32_e32 v3, 16, v7
	v_mul_f32_e32 v6, 0xbfb8aa3b, v3
	v_exp_f32_e32 v6, v6
	v_mul_f32_e32 v9, v10, v11
	v_cvt_pk_bf16_f32 v8, v8, v9
	v_mov_b32_e32 v10, v73
	v_add_f32_e32 v6, 1.0, v6
	v_rcp_f32_e32 v13, v6
	s_nop 0
	v_pk_mul_f32 v[12:13], v[12:13], v[2:3]
	v_and_b32_e32 v3, 0xffff0000, v7
	v_mul_f32_e32 v6, 0xbfb8aa3b, v3
	v_exp_f32_e32 v7, v6
	v_mov_b32_e32 v6, v79
	v_mul_f32_e32 v9, v12, v13
	v_mov_b32_e32 v12, v74
	v_add_f32_e32 v7, 1.0, v7
	v_rcp_f32_e32 v7, v7
	s_nop 0
	v_pk_mul_f32 v[6:7], v[6:7], v[2:3]
	s_nop 0
	v_mul_f32_e32 v3, v6, v7
	v_cvt_pk_bf16_f32 v9, v9, v3
	global_store_dwordx2 v[4:5], v[8:9], off offset:256
	s_waitcnt vmcnt(15)
	v_mov_b64_e32 v[6:7], v[124:125]
	v_lshlrev_b32_e32 v3, 16, v6
	v_mul_f32_e32 v8, 0xbfb8aa3b, v3
	v_exp_f32_e32 v8, v8
	s_nop 0
	v_add_f32_e32 v8, 1.0, v8
	v_rcp_f32_e32 v9, v8
	v_mov_b32_e32 v8, v72
	v_pk_mul_f32 v[8:9], v[8:9], v[2:3]
	v_and_b32_e32 v3, 0xffff0000, v6
	v_mul_f32_e32 v6, 0xbfb8aa3b, v3
	v_exp_f32_e32 v6, v6
	v_mul_f32_e32 v8, v8, v9
	v_add_f32_e32 v6, 1.0, v6
	v_rcp_f32_e32 v11, v6
	s_nop 0
	v_pk_mul_f32 v[10:11], v[10:11], v[2:3]
	v_lshlrev_b32_e32 v3, 16, v7
	v_mul_f32_e32 v6, 0xbfb8aa3b, v3
	v_exp_f32_e32 v6, v6
	v_mul_f32_e32 v9, v10, v11
	v_cvt_pk_bf16_f32 v8, v8, v9
	v_mov_b32_e32 v10, v69
	v_add_f32_e32 v6, 1.0, v6
	v_rcp_f32_e32 v13, v6
	s_nop 0
	v_pk_mul_f32 v[12:13], v[12:13], v[2:3]
	v_and_b32_e32 v3, 0xffff0000, v7
	v_mul_f32_e32 v6, 0xbfb8aa3b, v3
	v_exp_f32_e32 v7, v6
	v_mov_b32_e32 v6, v75
	v_mul_f32_e32 v9, v12, v13
	v_mov_b32_e32 v12, v70
	v_add_f32_e32 v7, 1.0, v7
	v_rcp_f32_e32 v7, v7
	s_nop 0
	v_pk_mul_f32 v[6:7], v[6:7], v[2:3]
	s_nop 0
	v_mul_f32_e32 v3, v6, v7
	v_cvt_pk_bf16_f32 v9, v9, v3
	global_store_dwordx2 v[4:5], v[8:9], off offset:288
	s_waitcnt vmcnt(15)
	v_mov_b64_e32 v[6:7], v[126:127]
	v_lshlrev_b32_e32 v3, 16, v6
	v_mul_f32_e32 v8, 0xbfb8aa3b, v3
	v_exp_f32_e32 v8, v8
	s_nop 0
	v_add_f32_e32 v8, 1.0, v8
	v_rcp_f32_e32 v9, v8
	v_mov_b32_e32 v8, v68
	v_pk_mul_f32 v[8:9], v[8:9], v[2:3]
	v_and_b32_e32 v3, 0xffff0000, v6
	v_mul_f32_e32 v6, 0xbfb8aa3b, v3
	v_exp_f32_e32 v6, v6
	v_mul_f32_e32 v8, v8, v9
	v_add_f32_e32 v6, 1.0, v6
	v_rcp_f32_e32 v11, v6
	s_nop 0
	v_pk_mul_f32 v[10:11], v[10:11], v[2:3]
	v_lshlrev_b32_e32 v3, 16, v7
	v_mul_f32_e32 v6, 0xbfb8aa3b, v3
	v_exp_f32_e32 v6, v6
	v_mul_f32_e32 v9, v10, v11
	v_cvt_pk_bf16_f32 v8, v8, v9
	v_mov_b32_e32 v10, v65
	v_add_f32_e32 v6, 1.0, v6
	v_rcp_f32_e32 v13, v6
	s_nop 0
	v_pk_mul_f32 v[12:13], v[12:13], v[2:3]
	v_and_b32_e32 v3, 0xffff0000, v7
	v_mul_f32_e32 v6, 0xbfb8aa3b, v3
	v_exp_f32_e32 v7, v6
	v_mov_b32_e32 v6, v71
	v_mul_f32_e32 v9, v12, v13
	v_mov_b32_e32 v12, v66
	v_add_f32_e32 v7, 1.0, v7
	v_rcp_f32_e32 v7, v7
	s_nop 0
	v_pk_mul_f32 v[6:7], v[6:7], v[2:3]
	s_nop 0
	v_mul_f32_e32 v3, v6, v7
	v_cvt_pk_bf16_f32 v9, v9, v3
	global_store_dwordx2 v[4:5], v[8:9], off offset:320
	s_waitcnt vmcnt(15)
	v_mov_b64_e32 v[6:7], v[128:129]
	v_lshlrev_b32_e32 v3, 16, v6
	v_mul_f32_e32 v8, 0xbfb8aa3b, v3
	v_exp_f32_e32 v8, v8
	s_nop 0
	v_add_f32_e32 v8, 1.0, v8
	v_rcp_f32_e32 v9, v8
	v_mov_b32_e32 v8, v64
	v_pk_mul_f32 v[8:9], v[8:9], v[2:3]
	v_and_b32_e32 v3, 0xffff0000, v6
	v_mul_f32_e32 v6, 0xbfb8aa3b, v3
	v_exp_f32_e32 v6, v6
	v_mul_f32_e32 v8, v8, v9
	v_add_f32_e32 v6, 1.0, v6
	v_rcp_f32_e32 v11, v6
	s_nop 0
	v_pk_mul_f32 v[10:11], v[10:11], v[2:3]
	v_lshlrev_b32_e32 v3, 16, v7
	v_mul_f32_e32 v6, 0xbfb8aa3b, v3
	v_exp_f32_e32 v6, v6
	v_mul_f32_e32 v9, v10, v11
	v_cvt_pk_bf16_f32 v8, v8, v9
	v_mov_b32_e32 v10, v45
	v_add_f32_e32 v6, 1.0, v6
	v_rcp_f32_e32 v13, v6
	s_nop 0
	v_pk_mul_f32 v[12:13], v[12:13], v[2:3]
	v_and_b32_e32 v3, 0xffff0000, v7
	v_mul_f32_e32 v6, 0xbfb8aa3b, v3
	v_exp_f32_e32 v7, v6
	v_mov_b32_e32 v6, v67
	v_mul_f32_e32 v9, v12, v13
	v_mov_b32_e32 v12, v46
	v_add_f32_e32 v7, 1.0, v7
	v_rcp_f32_e32 v7, v7
	s_nop 0
	v_pk_mul_f32 v[6:7], v[6:7], v[2:3]
	s_nop 0
	v_mul_f32_e32 v3, v6, v7
	v_cvt_pk_bf16_f32 v9, v9, v3
	global_store_dwordx2 v[4:5], v[8:9], off offset:352
	s_waitcnt vmcnt(15)
	v_mov_b64_e32 v[6:7], v[130:131]
	v_lshlrev_b32_e32 v3, 16, v6
	v_mul_f32_e32 v8, 0xbfb8aa3b, v3
	v_exp_f32_e32 v8, v8
	s_nop 0
	v_add_f32_e32 v8, 1.0, v8
	v_rcp_f32_e32 v9, v8
	v_mov_b32_e32 v8, v44
	v_pk_mul_f32 v[8:9], v[8:9], v[2:3]
	v_and_b32_e32 v3, 0xffff0000, v6
	v_mul_f32_e32 v6, 0xbfb8aa3b, v3
	v_exp_f32_e32 v6, v6
	v_mul_f32_e32 v8, v8, v9
	v_add_f32_e32 v6, 1.0, v6
	v_rcp_f32_e32 v11, v6
	s_nop 0
	v_pk_mul_f32 v[10:11], v[10:11], v[2:3]
	v_lshlrev_b32_e32 v3, 16, v7
	v_mul_f32_e32 v6, 0xbfb8aa3b, v3
	v_exp_f32_e32 v6, v6
	v_mul_f32_e32 v9, v10, v11
	v_cvt_pk_bf16_f32 v8, v8, v9
	v_mov_b32_e32 v10, v41
	v_add_f32_e32 v6, 1.0, v6
	v_rcp_f32_e32 v13, v6
	s_nop 0
	v_pk_mul_f32 v[12:13], v[12:13], v[2:3]
	v_and_b32_e32 v3, 0xffff0000, v7
	v_mul_f32_e32 v6, 0xbfb8aa3b, v3
	v_exp_f32_e32 v7, v6
	v_mov_b32_e32 v6, v47
	v_mul_f32_e32 v9, v12, v13
	v_mov_b32_e32 v12, v42
	v_add_f32_e32 v7, 1.0, v7
	v_rcp_f32_e32 v7, v7
	s_nop 0
	v_pk_mul_f32 v[6:7], v[6:7], v[2:3]
	s_nop 0
	v_mul_f32_e32 v3, v6, v7
	v_cvt_pk_bf16_f32 v9, v9, v3
	global_store_dwordx2 v[4:5], v[8:9], off offset:384
	s_waitcnt vmcnt(15)
	v_mov_b64_e32 v[6:7], v[162:163]
	v_lshlrev_b32_e32 v3, 16, v6
	v_mul_f32_e32 v8, 0xbfb8aa3b, v3
	v_exp_f32_e32 v8, v8
	s_nop 0
	v_add_f32_e32 v8, 1.0, v8
	v_rcp_f32_e32 v9, v8
	v_mov_b32_e32 v8, v40
	v_pk_mul_f32 v[8:9], v[8:9], v[2:3]
	v_and_b32_e32 v3, 0xffff0000, v6
	v_mul_f32_e32 v6, 0xbfb8aa3b, v3
	v_exp_f32_e32 v6, v6
	v_mul_f32_e32 v8, v8, v9
	v_add_f32_e32 v6, 1.0, v6
	v_rcp_f32_e32 v11, v6
	s_nop 0
	v_pk_mul_f32 v[10:11], v[10:11], v[2:3]
	v_lshlrev_b32_e32 v3, 16, v7
	v_mul_f32_e32 v6, 0xbfb8aa3b, v3
	v_exp_f32_e32 v6, v6
	v_mul_f32_e32 v9, v10, v11
	v_cvt_pk_bf16_f32 v8, v8, v9
	v_mov_b32_e32 v10, v37
	v_add_f32_e32 v6, 1.0, v6
	v_rcp_f32_e32 v13, v6
	s_nop 0
	v_pk_mul_f32 v[12:13], v[12:13], v[2:3]
	v_and_b32_e32 v3, 0xffff0000, v7
	v_mul_f32_e32 v6, 0xbfb8aa3b, v3
	v_exp_f32_e32 v7, v6
	v_mov_b32_e32 v6, v43
	v_mul_f32_e32 v9, v12, v13
	v_mov_b32_e32 v12, v38
	v_add_f32_e32 v7, 1.0, v7
	v_rcp_f32_e32 v7, v7
	s_nop 0
	v_pk_mul_f32 v[6:7], v[6:7], v[2:3]
	s_nop 0
	v_mul_f32_e32 v3, v6, v7
	v_cvt_pk_bf16_f32 v9, v9, v3
	global_store_dwordx2 v[4:5], v[8:9], off offset:416
	s_waitcnt vmcnt(15)
	v_mov_b64_e32 v[6:7], v[164:165]
	v_lshlrev_b32_e32 v3, 16, v6
	v_mul_f32_e32 v8, 0xbfb8aa3b, v3
	v_exp_f32_e32 v8, v8
	s_nop 0
	v_add_f32_e32 v8, 1.0, v8
	v_rcp_f32_e32 v9, v8
	v_mov_b32_e32 v8, v36
	v_pk_mul_f32 v[8:9], v[8:9], v[2:3]
	v_and_b32_e32 v3, 0xffff0000, v6
	v_mul_f32_e32 v6, 0xbfb8aa3b, v3
	v_exp_f32_e32 v6, v6
	v_mul_f32_e32 v8, v8, v9
	v_add_f32_e32 v6, 1.0, v6
	v_rcp_f32_e32 v11, v6
	s_nop 0
	v_pk_mul_f32 v[10:11], v[10:11], v[2:3]
	v_lshlrev_b32_e32 v3, 16, v7
	v_mul_f32_e32 v6, 0xbfb8aa3b, v3
	v_exp_f32_e32 v6, v6
	v_mul_f32_e32 v9, v10, v11
	v_cvt_pk_bf16_f32 v8, v8, v9
	v_mov_b32_e32 v10, v34
	v_add_f32_e32 v6, 1.0, v6
	v_rcp_f32_e32 v13, v6
	s_nop 0
	v_pk_mul_f32 v[12:13], v[12:13], v[2:3]
	v_and_b32_e32 v3, 0xffff0000, v7
	v_mul_f32_e32 v6, 0xbfb8aa3b, v3
	v_exp_f32_e32 v7, v6
	v_mov_b32_e32 v6, v39
	v_mul_f32_e32 v9, v12, v13
	v_add_f32_e32 v7, 1.0, v7
	v_rcp_f32_e32 v7, v7
	s_nop 0
	v_pk_mul_f32 v[6:7], v[6:7], v[2:3]
	s_nop 0
	v_mul_f32_e32 v3, v6, v7
	v_cvt_pk_bf16_f32 v9, v9, v3
	global_store_dwordx2 v[4:5], v[8:9], off offset:448
	v_mov_b32_e32 v8, v33
	s_waitcnt vmcnt(15)
	v_mov_b64_e32 v[0:1], v[166:167]
	v_lshlrev_b32_e32 v3, 16, v0
	v_mul_f32_e32 v6, 0xbfb8aa3b, v3
	v_exp_f32_e32 v6, v6
	s_nop 0
	v_add_f32_e32 v6, 1.0, v6
	v_rcp_f32_e32 v7, v6
	v_mov_b32_e32 v6, v32
	v_pk_mul_f32 v[6:7], v[6:7], v[2:3]
	v_and_b32_e32 v3, 0xffff0000, v0
	v_mul_f32_e32 v0, 0xbfb8aa3b, v3
	v_exp_f32_e32 v0, v0
	v_mul_f32_e32 v6, v6, v7
	v_add_f32_e32 v0, 1.0, v0
	v_rcp_f32_e32 v9, v0
	s_nop 0
	v_pk_mul_f32 v[8:9], v[8:9], v[2:3]
	v_lshlrev_b32_e32 v3, 16, v1
	v_mul_f32_e32 v0, 0xbfb8aa3b, v3
	v_exp_f32_e32 v0, v0
	v_mul_f32_e32 v7, v8, v9
	v_cvt_pk_bf16_f32 v6, v6, v7
	v_add_f32_e32 v0, 1.0, v0
	v_rcp_f32_e32 v11, v0
	v_mov_b32_e32 v0, v35
	v_pk_mul_f32 v[10:11], v[10:11], v[2:3]
	v_and_b32_e32 v3, 0xffff0000, v1
	v_mul_f32_e32 v1, 0xbfb8aa3b, v3
	v_exp_f32_e32 v1, v1
	v_mul_f32_e32 v7, v10, v11
	v_add_f32_e32 v1, 1.0, v1
	v_rcp_f32_e32 v1, v1
	s_nop 0
	v_pk_mul_f32 v[0:1], v[0:1], v[2:3]
	s_nop 0
	v_mul_f32_e32 v0, v0, v1
	v_cvt_pk_bf16_f32 v7, v7, v0
	global_store_dwordx2 v[4:5], v[6:7], off offset:480
	s_cbranch_vccnz .LBB0_1105

.LBB0_1093:
	v_add3_u32 v244, s12, v195, v219
	v_cvt_pk_bf16_f32 v60, v120, v121
	v_cvt_pk_bf16_f32 v61, v122, v123
	v_cvt_pk_bf16_f32 v62, v180, v181
	v_cvt_pk_bf16_f32 v63, v182, v183
	ds_read_b64_tr_b16 v[104:105], v244 offset:34816
	ds_read_b64_tr_b16 v[106:107], v244 offset:43520
	ds_read_b64_tr_b16 v[110:111], v244 offset:43552
	ds_read_b64_tr_b16 v[108:109], v244 offset:34848
	ds_read_b64_tr_b16 v[120:121], v244 offset:34880
	ds_read_b64_tr_b16 v[180:181], v244 offset:34912
	ds_read_b64_tr_b16 v[122:123], v244 offset:43584
	ds_read_b64_tr_b16 v[182:183], v244 offset:43616
	s_waitcnt lgkmcnt(6)
	v_mfma_f32_16x16x32_bf16 v[100:103], v[104:107], v[60:63], v[100:103]
	ds_read_b64_tr_b16 v[104:105], v244 offset:34944
	ds_read_b64_tr_b16 v[106:107], v244 offset:43648
	v_mul_f32_e32 v59, v59, v243
	s_add_i32 s58, s58, 1
	s_waitcnt lgkmcnt(6)
	v_mfma_f32_16x16x32_bf16 v[96:99], v[108:111], v[60:63], v[96:99]
	s_sub_i32 s16, s16, 64
	s_add_u32 s52, s52, 0x20000
	s_addc_u32 s53, s53, 0
	s_waitcnt lgkmcnt(3)
	v_mfma_f32_16x16x32_bf16 v[52:55], v[120:123], v[60:63], v[52:55]
	v_add_u32_e32 v236, 64, v236
	s_cmpk_eq_i32 s16, 0xfe00
	s_waitcnt lgkmcnt(2)
	v_mfma_f32_16x16x32_bf16 v[48:51], v[180:183], v[60:63], v[48:51]
	ds_read_b64_tr_b16 v[110:111], v244 offset:43680
	ds_read_b64_tr_b16 v[108:109], v244 offset:34976
	ds_read_b64_tr_b16 v[120:121], v244 offset:35008
	ds_read_b64_tr_b16 v[180:181], v244 offset:35040
	ds_read_b64_tr_b16 v[122:123], v244 offset:43712
	ds_read_b64_tr_b16 v[182:183], v244 offset:43744
	s_waitcnt lgkmcnt(6)
	v_mfma_f32_16x16x32_bf16 v[92:95], v[104:107], v[60:63], v[92:95]
	ds_read_b64_tr_b16 v[104:105], v244 offset:35072
	ds_read_b64_tr_b16 v[106:107], v244 offset:43776
	s_waitcnt lgkmcnt(6)
	v_mfma_f32_16x16x32_bf16 v[88:91], v[108:111], v[60:63], v[88:91]
	s_waitcnt lgkmcnt(3)
	v_mfma_f32_16x16x32_bf16 v[84:87], v[120:123], v[60:63], v[84:87]
	s_waitcnt lgkmcnt(2)
	v_mfma_f32_16x16x32_bf16 v[80:83], v[180:183], v[60:63], v[80:83]
	ds_read_b64_tr_b16 v[110:111], v244 offset:43808
	ds_read_b64_tr_b16 v[108:109], v244 offset:35104
	ds_read_b64_tr_b16 v[120:121], v244 offset:35136
	ds_read_b64_tr_b16 v[180:181], v244 offset:35168
	ds_read_b64_tr_b16 v[122:123], v244 offset:43840
	ds_read_b64_tr_b16 v[182:183], v244 offset:43872
	s_waitcnt lgkmcnt(6)
	v_mfma_f32_16x16x32_bf16 v[76:79], v[104:107], v[60:63], v[76:79]
	ds_read_b64_tr_b16 v[104:105], v244 offset:35200
	ds_read_b64_tr_b16 v[106:107], v244 offset:43904
	s_waitcnt lgkmcnt(6)
	v_mfma_f32_16x16x32_bf16 v[72:75], v[108:111], v[60:63], v[72:75]
	s_waitcnt lgkmcnt(3)
	v_mfma_f32_16x16x32_bf16 v[68:71], v[120:123], v[60:63], v[68:71]
	s_waitcnt lgkmcnt(2)
	v_mfma_f32_16x16x32_bf16 v[64:67], v[180:183], v[60:63], v[64:67]
	ds_read_b64_tr_b16 v[110:111], v244 offset:43936
	ds_read_b64_tr_b16 v[108:109], v244 offset:35232
	ds_read_b64_tr_b16 v[120:121], v244 offset:35264
	ds_read_b64_tr_b16 v[180:181], v244 offset:35296
	ds_read_b64_tr_b16 v[122:123], v244 offset:43968
	ds_read_b64_tr_b16 v[182:183], v244 offset:44000
	v_cvt_pk_bf16_f32 v56, v116, v117
	v_cvt_pk_bf16_f32 v57, v118, v119
	s_waitcnt lgkmcnt(6)
	v_mfma_f32_16x16x32_bf16 v[44:47], v[104:107], v[60:63], v[44:47]
	v_cvt_pk_bf16_f32 v58, v178, v179
	v_cvt_pk_bf16_f32 v59, v242, v59
	ds_read_b64_tr_b16 v[106:107], v244 offset:60928
	ds_read_b64_tr_b16 v[104:105], v244 offset:52224
	s_waitcnt lgkmcnt(6)
	v_mfma_f32_16x16x32_bf16 v[40:43], v[108:111], v[60:63], v[40:43]
	s_waitcnt lgkmcnt(3)
	v_mfma_f32_16x16x32_bf16 v[36:39], v[120:123], v[60:63], v[36:39]
	s_waitcnt lgkmcnt(2)
	v_mfma_f32_16x16x32_bf16 v[32:35], v[180:183], v[60:63], v[32:35]
	ds_read_b64_tr_b16 v[62:63], v244 offset:60960
	ds_read_b64_tr_b16 v[60:61], v244 offset:52256
	ds_read_b64_tr_b16 v[108:109], v244 offset:52288
	ds_read_b64_tr_b16 v[116:117], v244 offset:52320
	ds_read_b64_tr_b16 v[110:111], v244 offset:60992
	ds_read_b64_tr_b16 v[118:119], v244 offset:61024
	s_waitcnt lgkmcnt(4)
	v_mfma_f32_16x16x32_bf16 v[96:99], v[60:63], v[56:59], v[96:99]
	ds_read_b64_tr_b16 v[60:61], v244 offset:52352
	ds_read_b64_tr_b16 v[62:63], v244 offset:61056
	v_mfma_f32_16x16x32_bf16 v[100:103], v[104:107], v[56:59], v[100:103]
	s_waitcnt lgkmcnt(3)
	v_mfma_f32_16x16x32_bf16 v[52:55], v[108:111], v[56:59], v[52:55]
	s_waitcnt lgkmcnt(2)
	v_mfma_f32_16x16x32_bf16 v[48:51], v[116:119], v[56:59], v[48:51]
	ds_read_b64_tr_b16 v[106:107], v244 offset:61088
	ds_read_b64_tr_b16 v[104:105], v244 offset:52384
	ds_read_b64_tr_b16 v[108:109], v244 offset:52416
	ds_read_b64_tr_b16 v[116:117], v244 offset:52448
	ds_read_b64_tr_b16 v[110:111], v244 offset:61120
	ds_read_b64_tr_b16 v[118:119], v244 offset:61152
	s_waitcnt lgkmcnt(6)
	v_mfma_f32_16x16x32_bf16 v[92:95], v[60:63], v[56:59], v[92:95]
	ds_read_b64_tr_b16 v[60:61], v244 offset:52480
	ds_read_b64_tr_b16 v[62:63], v244 offset:61184
	s_waitcnt lgkmcnt(6)
	v_mfma_f32_16x16x32_bf16 v[88:91], v[104:107], v[56:59], v[88:91]
	s_waitcnt lgkmcnt(3)
	v_mfma_f32_16x16x32_bf16 v[84:87], v[108:111], v[56:59], v[84:87]
	s_waitcnt lgkmcnt(2)
	v_mfma_f32_16x16x32_bf16 v[80:83], v[116:119], v[56:59], v[80:83]
	ds_read_b64_tr_b16 v[106:107], v244 offset:61216
	ds_read_b64_tr_b16 v[104:105], v244 offset:52512
	ds_read_b64_tr_b16 v[108:109], v244 offset:52544
	ds_read_b64_tr_b16 v[116:117], v244 offset:52576
	ds_read_b64_tr_b16 v[110:111], v244 offset:61248
	ds_read_b64_tr_b16 v[118:119], v244 offset:61280
	s_waitcnt lgkmcnt(6)
	v_mfma_f32_16x16x32_bf16 v[76:79], v[60:63], v[56:59], v[76:79]
	ds_read_b64_tr_b16 v[60:61], v244 offset:52608
	s_waitcnt lgkmcnt(5)
	v_mfma_f32_16x16x32_bf16 v[72:75], v[104:107], v[56:59], v[72:75]
	ds_read_b64_tr_b16 v[62:63], v244 offset:61312
	ds_read_b64_tr_b16 v[106:107], v244 offset:61344
	s_waitcnt lgkmcnt(4)
	v_mfma_f32_16x16x32_bf16 v[68:71], v[108:111], v[56:59], v[68:71]
	s_waitcnt lgkmcnt(3)
	v_mfma_f32_16x16x32_bf16 v[64:67], v[116:119], v[56:59], v[64:67]
	ds_read_b64_tr_b16 v[104:105], v244 offset:52640
	ds_read_b64_tr_b16 v[108:109], v244 offset:52672
	ds_read_b64_tr_b16 v[116:117], v244 offset:52704
	ds_read_b64_tr_b16 v[110:111], v244 offset:61376
	ds_read_b64_tr_b16 v[118:119], v244 offset:61408
	s_waitcnt vmcnt(0)
	s_waitcnt lgkmcnt(0)
	v_mfma_f32_16x16x32_bf16 v[44:47], v[60:63], v[56:59], v[44:47]
	s_barrier
	v_mfma_f32_16x16x32_bf16 v[40:43], v[104:107], v[56:59], v[40:43]
	v_mfma_f32_16x16x32_bf16 v[36:39], v[108:111], v[56:59], v[36:39]
	v_mfma_f32_16x16x32_bf16 v[32:35], v[116:119], v[56:59], v[32:35]
	s_cbranch_scc1 .LBB0_1083
